# grid barrier: L2 write-back started by every workgroup at arrival (early release write-back)
# baseline (speedup 1.0000x reference)
.LBB0_318:
	s_mov_b64 s[36:37], exec
	v_mbcnt_lo_u32_b32 v2, s36, 0
	v_mbcnt_hi_u32_b32 v2, s37, v2
	v_cmp_eq_u32_e32 vcc, 0, v2
	s_and_saveexec_b64 s[4:5], vcc
	s_cbranch_execz .LBB0_320
	s_bcnt1_i32_b64 s2, s[36:37]
	v_readlane_b32 s12, v253, 48
	v_mov_b32_e32 v4, s2
	v_readlane_b32 s13, v253, 49
	s_nop 4
	buffer_wbl2 sc1
	s_waitcnt vmcnt(0)
	global_atomic_add v4, v1, v4, s[12:13] sc0

.LBB0_544:
	s_mov_b64 s[6:7], exec
	v_mbcnt_lo_u32_b32 v0, s6, 0
	v_mbcnt_hi_u32_b32 v0, s7, v0
	v_cmp_eq_u32_e32 vcc, 0, v0
	s_and_saveexec_b64 s[4:5], vcc
	s_cbranch_execz .LBB0_546
	s_bcnt1_i32_b64 s2, s[6:7]
	v_readlane_b32 s6, v253, 48
	v_mov_b32_e32 v4, s2
	v_readlane_b32 s7, v253, 49
	s_nop 4
	buffer_wbl2 sc1
	s_waitcnt vmcnt(0)
	global_atomic_add v4, v1, v4, s[6:7] sc0
